# attention top-k removal block in VOP2/VOPC forms: selected bit from index difference, one cmp+cndmask per element; on top of v112
# speedup vs baseline: 1.0022x; 1.0022x over previous
.LBB0_1218:
	s_add_i32 s12, s33, -2
	v_cmp_ge_i32_e32 vcc, s12, v168
	s_nop 5
	ds_write2st64_b32 v157, v16, v17 offset1:8
	s_nop 0
	ds_write2st64_b32 v157, v0, v1 offset0:128 offset1:136
	ds_write2st64_b32 v157, v18, v19 offset0:16 offset1:24
	ds_write2st64_b32 v157, v2, v3 offset0:144 offset1:152
	ds_write2st64_b32 v157, v20, v21 offset0:32 offset1:40
	ds_write2st64_b32 v157, v4, v5 offset0:160 offset1:168
	ds_write2st64_b32 v157, v22, v23 offset0:48 offset1:56
	ds_write2st64_b32 v157, v6, v7 offset0:176 offset1:184
	ds_write2st64_b32 v157, v24, v25 offset0:64 offset1:72
	ds_write2st64_b32 v157, v8, v9 offset0:192 offset1:200
	ds_write2st64_b32 v157, v26, v27 offset0:80 offset1:88
	ds_write2st64_b32 v157, v10, v11 offset0:208 offset1:216
	ds_write2st64_b32 v157, v28, v29 offset0:96 offset1:104
	ds_write2st64_b32 v157, v12, v13 offset0:224 offset1:232
	ds_write2st64_b32 v157, v30, v31 offset0:112 offset1:120
	ds_write2st64_b32 v157, v14, v15 offset0:240 offset1:248
	s_and_b64 s[14:15], s[50:51], vcc
	v_mov_b32_e32 v0, -1
	v_mov_b32_e32 v1, -1
	s_waitcnt lgkmcnt(0)
	s_barrier
	s_and_saveexec_b64 s[0:1], s[14:15]
	ds_read_b32 v1, v173 offset:36864
	s_or_b64 exec, exec, s[0:1]
	v_cmp_gt_i32_e32 vcc, s12, v168
	s_and_saveexec_b64 s[0:1], vcc
	ds_read_b32 v0, v173 offset:36868
	s_or_b64 exec, exec, s[0:1]
	v_cmp_ge_i32_e32 vcc, s12, v175
	v_mov_b32_e32 v2, -1
	v_mov_b32_e32 v3, -1
	s_and_saveexec_b64 s[0:1], vcc
	ds_read_b32 v3, v173 offset:36872
	s_or_b64 exec, exec, s[0:1]
	v_cmp_ge_i32_e32 vcc, s12, v178
	s_and_saveexec_b64 s[0:1], vcc
	ds_read_b32 v2, v173 offset:36876
	s_or_b64 exec, exec, s[0:1]
	v_cmp_ge_i32_e32 vcc, s12, v188
	v_mov_b32_e32 v4, -1
	v_mov_b32_e32 v5, -1
	s_and_saveexec_b64 s[0:1], vcc
	ds_read_b32 v5, v173 offset:36880
	s_or_b64 exec, exec, s[0:1]
	v_cmp_ge_i32_e32 vcc, s12, v189
	s_and_saveexec_b64 s[0:1], vcc
	ds_read_b32 v4, v173 offset:36884
	s_or_b64 exec, exec, s[0:1]
	v_cmp_ge_i32_e32 vcc, s12, v190
	v_mov_b32_e32 v6, -1
	v_mov_b32_e32 v7, -1
	s_and_saveexec_b64 s[0:1], vcc
	ds_read_b32 v7, v173 offset:36888
	s_or_b64 exec, exec, s[0:1]
	v_cmp_ge_i32_e32 vcc, s12, v191
	s_and_saveexec_b64 s[0:1], vcc
	ds_read_b32 v6, v173 offset:36892
	s_or_b64 exec, exec, s[0:1]
	v_cmp_ge_i32_e32 vcc, s12, v192
	v_mov_b32_e32 v8, -1
	v_mov_b32_e32 v9, -1
	s_and_saveexec_b64 s[0:1], vcc
	ds_read_b32 v9, v173 offset:36896
	s_or_b64 exec, exec, s[0:1]
	v_cmp_ge_i32_e32 vcc, s12, v193
	s_and_saveexec_b64 s[0:1], vcc
	ds_read_b32 v8, v173 offset:36900
	s_or_b64 exec, exec, s[0:1]
	v_cmp_ge_i32_e32 vcc, s12, v194
	v_mov_b32_e32 v10, -1
	v_mov_b32_e32 v11, -1
	s_and_saveexec_b64 s[0:1], vcc
	ds_read_b32 v11, v173 offset:36904
	s_or_b64 exec, exec, s[0:1]
	v_cmp_ge_i32_e32 vcc, s12, v195
	s_and_saveexec_b64 s[0:1], vcc
	ds_read_b32 v10, v173 offset:36908
	s_or_b64 exec, exec, s[0:1]
	v_cmp_ge_i32_e32 vcc, s12, v196
	v_mov_b32_e32 v12, -1
	v_mov_b32_e32 v13, -1
	s_and_saveexec_b64 s[0:1], vcc
	ds_read_b32 v13, v173 offset:36912
	s_or_b64 exec, exec, s[0:1]
	v_cmp_ge_i32_e32 vcc, s12, v197
	s_and_saveexec_b64 s[0:1], vcc
	ds_read_b32 v12, v173 offset:36916
	s_or_b64 exec, exec, s[0:1]
	v_cmp_ge_i32_e32 vcc, s12, v198
	v_mov_b32_e32 v14, -1
	v_mov_b32_e32 v15, -1
	s_and_saveexec_b64 s[0:1], vcc
	ds_read_b32 v15, v173 offset:36920
	s_or_b64 exec, exec, s[0:1]
	v_cmp_ge_i32_e32 vcc, s12, v199
	s_and_saveexec_b64 s[0:1], vcc
	ds_read_b32 v14, v173 offset:36924
	s_or_b64 exec, exec, s[0:1]
	s_cmp_eq_u32 s33, 1
	s_cselect_b32 s0, 14, 13
	s_cmp_lg_u32 s33, 0
	s_cselect_b32 s12, s0, 15
	v_mov_b32_e32 v16, 0
	v_mov_b32_e32 v20, -1
	s_branch .LBB0_1252

.LBB0_1252:
	s_waitcnt lgkmcnt(0)
	v_max_i32_e32 v17, v1, v0
	v_max3_i32 v17, v17, v3, v2
	v_max3_i32 v17, v17, v5, v4
	v_max3_i32 v17, v17, v7, v6
	v_max3_i32 v17, v17, v9, v8
	v_max3_i32 v17, v17, v11, v10
	v_max3_i32 v17, v17, v13, v12
	v_max3_i32 v17, v17, v15, v14
	s_nop 1
	v_max_i32_dpp v17, v17, v17 quad_perm:[1,0,3,2] row_mask:0xf bank_mask:0xf bound_ctrl:1
	s_nop 1
	v_max_i32_dpp v17, v17, v17 quad_perm:[2,3,0,1] row_mask:0xf bank_mask:0xf bound_ctrl:1
	s_nop 1
	v_max_i32_dpp v19, v17, v17 row_half_mirror row_mask:0xf bank_mask:0xf bound_ctrl:1
	v_cmp_eq_u32_e32 vcc, v1, v19
	v_mov_b32_e32 v17, 0xff
	s_nop 0
	v_cndmask_b32_e32 v17, v17, v168, vcc
	v_min_i32_e32 v18, v17, v174
	v_cmp_eq_u32_e32 vcc, v0, v19
	s_nop 1
	v_cndmask_b32_e32 v17, v17, v18, vcc
	v_min_i32_e32 v18, v17, v175
	v_cmp_eq_u32_e32 vcc, v3, v19
	s_nop 1
	v_cndmask_b32_e32 v17, v17, v18, vcc
	v_min_i32_e32 v18, v17, v178
	v_cmp_eq_u32_e32 vcc, v2, v19
	s_nop 1
	v_cndmask_b32_e32 v17, v17, v18, vcc
	v_min_i32_e32 v18, v17, v188
	v_cmp_eq_u32_e32 vcc, v5, v19
	s_nop 1
	v_cndmask_b32_e32 v17, v17, v18, vcc
	v_min_i32_e32 v18, v17, v189
	v_cmp_eq_u32_e32 vcc, v4, v19
	s_nop 1
	v_cndmask_b32_e32 v17, v17, v18, vcc
	v_min_i32_e32 v18, v17, v190
	v_cmp_eq_u32_e32 vcc, v7, v19
	s_nop 1
	v_cndmask_b32_e32 v17, v17, v18, vcc
	v_min_i32_e32 v18, v17, v191
	v_cmp_eq_u32_e32 vcc, v6, v19
	s_nop 1
	v_cndmask_b32_e32 v17, v17, v18, vcc
	v_min_i32_e32 v18, v17, v192
	v_cmp_eq_u32_e32 vcc, v9, v19
	s_nop 1
	v_cndmask_b32_e32 v17, v17, v18, vcc
	v_min_i32_e32 v18, v17, v193
	v_cmp_eq_u32_e32 vcc, v8, v19
	s_nop 1
	v_cndmask_b32_e32 v17, v17, v18, vcc
	v_min_i32_e32 v18, v17, v194
	v_cmp_eq_u32_e32 vcc, v11, v19
	s_nop 1
	v_cndmask_b32_e32 v17, v17, v18, vcc
	v_min_i32_e32 v18, v17, v195
	v_cmp_eq_u32_e32 vcc, v10, v19
	s_nop 1
	v_cndmask_b32_e32 v17, v17, v18, vcc
	v_min_i32_e32 v18, v17, v196
	v_cmp_eq_u32_e32 vcc, v13, v19
	s_nop 1
	v_cndmask_b32_e32 v17, v17, v18, vcc
	v_min_i32_e32 v18, v17, v197
	v_cmp_eq_u32_e32 vcc, v12, v19
	s_nop 1
	v_cndmask_b32_e32 v17, v17, v18, vcc
	v_min_i32_e32 v18, v17, v198
	v_cmp_eq_u32_e32 vcc, v15, v19
	s_nop 1
	v_cndmask_b32_e32 v17, v17, v18, vcc
	v_min_i32_e32 v18, v17, v199
	v_cmp_eq_u32_e32 vcc, v14, v19
	s_nop 1
	v_cndmask_b32_e32 v17, v17, v18, vcc
	v_mov_b32_e32 v18, 0
	v_cmp_lt_i32_e32 vcc, -1, v19
	v_min_i32_dpp v17, v17, v17 quad_perm:[1,0,3,2] row_mask:0xf bank_mask:0xf bound_ctrl:1
	s_nop 1
	v_min_i32_dpp v17, v17, v17 quad_perm:[2,3,0,1] row_mask:0xf bank_mask:0xf bound_ctrl:1
	s_nop 1
	v_mov_b32_dpp v18, v17 row_half_mirror row_mask:0xf bank_mask:0xf
	s_and_saveexec_b64 s[0:1], vcc
	s_cbranch_execz .LBB0_1251
	v_min_i32_e32 v17, v17, v18
	v_sub_u32_e32 v18, v17, v168
	v_cmp_gt_u32_e32 vcc, 16, v18
	v_lshlrev_b32_e64 v19, v18, 1
	s_nop 0
	v_cndmask_b32_e32 v19, 0, v19, vcc
	v_or_b32_e32 v16, v16, v19
	v_cmp_eq_u32_e32 vcc, v168, v17
	s_nop 1
	v_cndmask_b32_e32 v1, v1, v20, vcc
	v_cmp_eq_u32_e32 vcc, v174, v17
	s_nop 1
	v_cndmask_b32_e32 v0, v0, v20, vcc
	v_cmp_eq_u32_e32 vcc, v175, v17
	s_nop 1
	v_cndmask_b32_e32 v3, v3, v20, vcc
	v_cmp_eq_u32_e32 vcc, v178, v17
	s_nop 1
	v_cndmask_b32_e32 v2, v2, v20, vcc
	v_cmp_eq_u32_e32 vcc, v188, v17
	s_nop 1
	v_cndmask_b32_e32 v5, v5, v20, vcc
	v_cmp_eq_u32_e32 vcc, v189, v17
	s_nop 1
	v_cndmask_b32_e32 v4, v4, v20, vcc
	v_cmp_eq_u32_e32 vcc, v190, v17
	s_nop 1
	v_cndmask_b32_e32 v7, v7, v20, vcc
	v_cmp_eq_u32_e32 vcc, v191, v17
	s_nop 1
	v_cndmask_b32_e32 v6, v6, v20, vcc
	v_cmp_eq_u32_e32 vcc, v192, v17
	s_nop 1
	v_cndmask_b32_e32 v9, v9, v20, vcc
	v_cmp_eq_u32_e32 vcc, v193, v17
	s_nop 1
	v_cndmask_b32_e32 v8, v8, v20, vcc
	v_cmp_eq_u32_e32 vcc, v194, v17
	s_nop 1
	v_cndmask_b32_e32 v11, v11, v20, vcc
	v_cmp_eq_u32_e32 vcc, v195, v17
	s_nop 1
	v_cndmask_b32_e32 v10, v10, v20, vcc
	v_cmp_eq_u32_e32 vcc, v196, v17
	s_nop 1
	v_cndmask_b32_e32 v13, v13, v20, vcc
	v_cmp_eq_u32_e32 vcc, v197, v17
	s_nop 1
	v_cndmask_b32_e32 v12, v12, v20, vcc
	v_cmp_eq_u32_e32 vcc, v198, v17
	s_nop 1
	v_cndmask_b32_e32 v15, v15, v20, vcc
	v_cmp_eq_u32_e32 vcc, v199, v17
	s_nop 1
	v_cndmask_b32_e32 v14, v14, v20, vcc
	s_branch .LBB0_1251
